# prep adaLN mod GEMV loop: 8 weight-row loads per trip issued up front with counted vmcnt instead of load-wait-use one at a time
# speedup vs baseline: 1.0175x; 1.0094x over previous
.LBB0_134:
	v_lshl_add_u64 v[120:121], v[24:25], 0, s[26:27]
	global_load_dwordx4 v[88:91], v[120:121], off
	v_lshl_add_u64 v[122:123], v[30:31], 0, s[26:27]
	global_load_dwordx4 v[92:95], v[122:123], off
	v_lshl_add_u64 v[120:121], v[34:35], 0, s[26:27]
	global_load_dwordx4 v[96:99], v[120:121], off
	v_lshl_add_u64 v[122:123], v[38:39], 0, s[26:27]
	global_load_dwordx4 v[100:103], v[122:123], off offset:-8
	v_lshl_add_u64 v[120:121], v[36:37], 0, s[26:27]
	global_load_dwordx4 v[104:107], v[120:121], off offset:-8
	v_lshl_add_u64 v[122:123], v[32:33], 0, s[26:27]
	global_load_dwordx4 v[108:111], v[122:123], off offset:-8
	v_lshl_add_u64 v[120:121], v[28:29], 0, s[26:27]
	global_load_dwordx4 v[112:115], v[120:121], off offset:-8
	v_lshl_add_u64 v[122:123], v[26:27], 0, s[26:27]
	global_load_dwordx4 v[116:119], v[122:123], off offset:-8
	v_add_u32_e32 v56, 0x1000, v45
	v_add_u32_e32 v57, 0x2000, v45
	ds_read2_b32 v[50:51], v45 offset1:16
	ds_read2_b32 v[52:53], v56 offset1:16
	ds_read2_b32 v[54:55], v57 offset1:16
	v_add_u32_e32 v14, 0x80, v14
	s_movk_i32 s21, 0x37f
	v_cmp_lt_i32_e32 vcc, s21, v14
	v_lshl_add_u64 v[24:25], v[24:25], 0, s[18:19]
	s_or_b64 s[28:29], vcc, s[28:29]
	s_waitcnt vmcnt(7) lgkmcnt(2)
	v_pk_fma_f32 v[4:5], v[88:89], v[50:51], v[4:5] op_sel_hi:[1,0,1]
	s_waitcnt lgkmcnt(1)
	v_pk_fma_f32 v[8:9], v[88:89], v[52:53], v[8:9] op_sel_hi:[1,0,1]
	s_waitcnt lgkmcnt(0)
	v_pk_fma_f32 v[46:47], v[88:89], v[54:55], v[0:1] op_sel_hi:[1,0,1]
	v_pk_fma_f32 v[6:7], v[90:91], v[50:51], v[6:7] op_sel_hi:[1,0,1]
	v_pk_fma_f32 v[10:11], v[90:91], v[52:53], v[10:11] op_sel_hi:[1,0,1]
	v_pk_fma_f32 v[48:49], v[90:91], v[54:55], v[2:3] op_sel_hi:[1,0,1]
	v_mov_b32_e32 v50, v51
	v_lshl_add_u64 v[30:31], v[30:31], 0, s[18:19]
	s_waitcnt vmcnt(6)
	v_pk_fma_f32 v[4:5], v[92:93], v[50:51], v[4:5] op_sel_hi:[1,0,1]
	v_pk_fma_f32 v[6:7], v[94:95], v[50:51], v[6:7] op_sel_hi:[1,0,1]
	v_mov_b32_e32 v50, v53
	v_pk_fma_f32 v[8:9], v[92:93], v[50:51], v[8:9] op_sel_hi:[1,0,1]
	v_pk_fma_f32 v[10:11], v[94:95], v[50:51], v[10:11] op_sel_hi:[1,0,1]
	v_mov_b32_e32 v50, v55
	v_pk_fma_f32 v[46:47], v[92:93], v[50:51], v[46:47] op_sel_hi:[1,0,1]
	v_pk_fma_f32 v[48:49], v[94:95], v[50:51], v[48:49] op_sel_hi:[1,0,1]
	ds_read2_b32 v[50:51], v45 offset0:32 offset1:48
	ds_read2_b32 v[52:53], v56 offset0:32 offset1:48
	ds_read2_b32 v[54:55], v57 offset0:32 offset1:48
	v_lshl_add_u64 v[34:35], v[34:35], 0, s[18:19]
	s_waitcnt vmcnt(5) lgkmcnt(2)
	v_pk_fma_f32 v[4:5], v[96:97], v[50:51], v[4:5] op_sel_hi:[1,0,1]
	s_waitcnt lgkmcnt(1)
	v_pk_fma_f32 v[8:9], v[96:97], v[52:53], v[8:9] op_sel_hi:[1,0,1]
	s_waitcnt lgkmcnt(0)
	v_pk_fma_f32 v[46:47], v[96:97], v[54:55], v[46:47] op_sel_hi:[1,0,1]
	v_pk_fma_f32 v[6:7], v[98:99], v[50:51], v[6:7] op_sel_hi:[1,0,1]
	v_pk_fma_f32 v[10:11], v[98:99], v[52:53], v[10:11] op_sel_hi:[1,0,1]
	v_pk_fma_f32 v[48:49], v[98:99], v[54:55], v[48:49] op_sel_hi:[1,0,1]
	v_mov_b32_e32 v50, v51
	v_lshl_add_u64 v[38:39], v[38:39], 0, s[18:19]
	s_waitcnt vmcnt(4)
	v_pk_fma_f32 v[4:5], v[100:101], v[50:51], v[4:5] op_sel_hi:[1,0,1]
	v_pk_fma_f32 v[6:7], v[102:103], v[50:51], v[6:7] op_sel_hi:[1,0,1]
	v_mov_b32_e32 v50, v53
	v_pk_fma_f32 v[8:9], v[100:101], v[50:51], v[8:9] op_sel_hi:[1,0,1]
	v_pk_fma_f32 v[10:11], v[102:103], v[50:51], v[10:11] op_sel_hi:[1,0,1]
	v_mov_b32_e32 v50, v55
	v_pk_fma_f32 v[46:47], v[100:101], v[50:51], v[46:47] op_sel_hi:[1,0,1]
	v_pk_fma_f32 v[48:49], v[102:103], v[50:51], v[48:49] op_sel_hi:[1,0,1]
	ds_read2_b32 v[50:51], v45 offset0:64 offset1:80
	ds_read2_b32 v[52:53], v56 offset0:64 offset1:80
	ds_read2_b32 v[54:55], v57 offset0:64 offset1:80
	v_lshl_add_u64 v[36:37], v[36:37], 0, s[18:19]
	s_waitcnt vmcnt(3) lgkmcnt(2)
	v_pk_fma_f32 v[4:5], v[104:105], v[50:51], v[4:5] op_sel_hi:[1,0,1]
	s_waitcnt lgkmcnt(1)
	v_pk_fma_f32 v[8:9], v[104:105], v[52:53], v[8:9] op_sel_hi:[1,0,1]
	s_waitcnt lgkmcnt(0)
	v_pk_fma_f32 v[46:47], v[104:105], v[54:55], v[46:47] op_sel_hi:[1,0,1]
	v_pk_fma_f32 v[6:7], v[106:107], v[50:51], v[6:7] op_sel_hi:[1,0,1]
	v_pk_fma_f32 v[10:11], v[106:107], v[52:53], v[10:11] op_sel_hi:[1,0,1]
	v_pk_fma_f32 v[48:49], v[106:107], v[54:55], v[48:49] op_sel_hi:[1,0,1]
	v_mov_b32_e32 v50, v51
	v_lshl_add_u64 v[32:33], v[32:33], 0, s[18:19]
	s_waitcnt vmcnt(2)
	v_pk_fma_f32 v[4:5], v[108:109], v[50:51], v[4:5] op_sel_hi:[1,0,1]
	v_pk_fma_f32 v[6:7], v[110:111], v[50:51], v[6:7] op_sel_hi:[1,0,1]
	v_mov_b32_e32 v50, v53
	v_pk_fma_f32 v[8:9], v[108:109], v[50:51], v[8:9] op_sel_hi:[1,0,1]
	v_pk_fma_f32 v[10:11], v[110:111], v[50:51], v[10:11] op_sel_hi:[1,0,1]
	v_mov_b32_e32 v50, v55
	v_pk_fma_f32 v[46:47], v[108:109], v[50:51], v[46:47] op_sel_hi:[1,0,1]
	v_pk_fma_f32 v[48:49], v[110:111], v[50:51], v[48:49] op_sel_hi:[1,0,1]
	ds_read2_b32 v[50:51], v45 offset0:96 offset1:112
	ds_read2_b32 v[52:53], v56 offset0:96 offset1:112
	ds_read2_b32 v[54:55], v57 offset0:96 offset1:112
	v_add_u32_e32 v45, 0x200, v45
	v_lshl_add_u64 v[28:29], v[28:29], 0, s[18:19]
	s_waitcnt vmcnt(1) lgkmcnt(2)
	v_pk_fma_f32 v[4:5], v[112:113], v[50:51], v[4:5] op_sel_hi:[1,0,1]
	s_waitcnt lgkmcnt(1)
	v_pk_fma_f32 v[8:9], v[112:113], v[52:53], v[8:9] op_sel_hi:[1,0,1]
	s_waitcnt lgkmcnt(0)
	v_pk_fma_f32 v[46:47], v[112:113], v[54:55], v[46:47] op_sel_hi:[1,0,1]
	v_pk_fma_f32 v[6:7], v[114:115], v[50:51], v[6:7] op_sel_hi:[1,0,1]
	v_pk_fma_f32 v[10:11], v[114:115], v[52:53], v[10:11] op_sel_hi:[1,0,1]
	v_pk_fma_f32 v[48:49], v[114:115], v[54:55], v[48:49] op_sel_hi:[1,0,1]
	v_mov_b32_e32 v50, v51
	v_lshl_add_u64 v[26:27], v[26:27], 0, s[18:19]
	s_waitcnt vmcnt(0)
	v_pk_fma_f32 v[4:5], v[116:117], v[50:51], v[4:5] op_sel_hi:[1,0,1]
	v_pk_fma_f32 v[6:7], v[118:119], v[50:51], v[6:7] op_sel_hi:[1,0,1]
	v_mov_b32_e32 v50, v53
	v_pk_fma_f32 v[8:9], v[116:117], v[50:51], v[8:9] op_sel_hi:[1,0,1]
	v_pk_fma_f32 v[10:11], v[118:119], v[50:51], v[10:11] op_sel_hi:[1,0,1]
	v_mov_b32_e32 v50, v55
	v_pk_fma_f32 v[0:1], v[116:117], v[50:51], v[46:47] op_sel_hi:[1,0,1]
	v_pk_fma_f32 v[2:3], v[118:119], v[50:51], v[48:49] op_sel_hi:[1,0,1]
	s_andn2_b64 exec, exec, s[28:29]
	s_cbranch_execnz .LBB0_134
	s_or_b64 exec, exec, s[28:29]
